# E8: E1 + attention loop LDS-DMA addresses via SGPR base + per-lane 32-bit offset (removes 5 v_lshl_add_u64 per 2 tiles)
# baseline (speedup 1.0000x reference)
.LBB0_730:
	s_lshl_b64 s[46:47], s[46:47], 1
	s_add_u32 s46, s54, s46
	s_addc_u32 s47, s55, s47
	s_add_u32 s46, s46, s28
	s_addc_u32 s47, s47, s29
	s_add_u32 s46, s46, s24
	s_addc_u32 s47, s47, s25
	s_lshl_b64 s[44:45], s[44:45], 1
	s_add_u32 s28, s44, s28
	s_addc_u32 s29, s45, s29
	v_exp_f32_e32 v52, v4
	v_and_b32_e32 v4, 3, v90
	s_add_u32 s24, s28, s24
	v_exp_f32_e32 v53, v5
	v_lshlrev_b32_e32 v4, 4, v4
	v_mov_b32_e32 v5, v2
	s_addc_u32 s25, s29, s25
	v_lshlrev_b32_e32 v0, 1, v90
	v_lshl_add_u64 v[4:5], s[24:25], 0, v[4:5]
	s_lshl_b32 s24, s60, 6
	v_exp_f32_e32 v68, v20
	v_exp_f32_e32 v69, v21
	v_exp_f32_e32 v70, v22
	v_exp_f32_e32 v71, v23
	v_exp_f32_e32 v72, v24
	v_exp_f32_e32 v73, v25
	v_exp_f32_e32 v74, v26
	v_exp_f32_e32 v75, v27
	v_exp_f32_e32 v76, v28
	v_exp_f32_e32 v77, v29
	v_exp_f32_e32 v78, v30
	v_exp_f32_e32 v79, v31
	v_exp_f32_e32 v80, v32
	v_exp_f32_e32 v81, v33
	v_exp_f32_e32 v82, v34
	v_exp_f32_e32 v83, v35
	v_exp_f32_e32 v54, v6
	v_exp_f32_e32 v55, v7
	v_exp_f32_e32 v56, v8
	v_exp_f32_e32 v57, v9
	v_exp_f32_e32 v58, v10
	v_exp_f32_e32 v59, v11
	v_exp_f32_e32 v60, v12
	v_exp_f32_e32 v61, v13
	v_exp_f32_e32 v62, v14
	v_exp_f32_e32 v63, v15
	v_exp_f32_e32 v64, v16
	v_exp_f32_e32 v65, v17
	v_exp_f32_e32 v66, v18
	v_exp_f32_e32 v67, v19
	v_and_b32_e32 v194, 32, v0
	v_lshlrev_b32_e32 v0, 4, v90
	s_and_b32 s24, s24, 0x3000
	v_and_b32_e32 v0, 0xc0, v0
	v_lshl_or_b32 v6, v91, 8, s24
	v_mov_b32_e32 v7, v2
	v_lshl_or_b32 v3, v189, 8, v0
	v_add_u32_e32 v0, 0, v194
	v_lshl_add_u64 v[4:5], v[4:5], 0, v[6:7]
	v_mov_b32_e32 v192, 0
	v_add3_u32 v190, v0, v193, v3
	v_lshl_add_u64 v[0:1], s[46:47], 0, v[88:89]
	v_lshl_add_u64 v[184:185], s[38:39], 0, v[4:5]
	s_movk_i32 s29, 0x4000
	s_movk_i32 s25, 0x2000
	s_mov_b32 s45, 0
	s_mov_b32 s24, -1
	v_mov_b32_e32 v4, 0
	v_mov_b32_e32 v5, v192
	v_mov_b32_e32 v6, v192
	v_mov_b32_e32 v7, v192
	v_mov_b32_e32 v8, v192
	v_mov_b32_e32 v9, v192
	v_mov_b32_e32 v10, v192
	v_mov_b32_e32 v11, v192
	v_mov_b32_e32 v12, v192
	v_mov_b32_e32 v13, v192
	v_mov_b32_e32 v14, v192
	v_mov_b32_e32 v15, v192
	v_mov_b32_e32 v16, v192
	v_mov_b32_e32 v17, v192
	v_mov_b32_e32 v18, v192
	v_mov_b32_e32 v19, v192
	v_mov_b32_e32 v20, 0
	v_mov_b32_e32 v21, v192
	v_mov_b32_e32 v22, v192
	v_mov_b32_e32 v23, v192
	v_mov_b32_e32 v24, v192
	v_mov_b32_e32 v25, v192
	v_mov_b32_e32 v26, v192
	v_mov_b32_e32 v27, v192
	v_mov_b32_e32 v28, v192
	v_mov_b32_e32 v29, v192
	v_mov_b32_e32 v30, v192
	v_mov_b32_e32 v31, v192
	v_mov_b32_e32 v32, v192
	v_mov_b32_e32 v33, v192
	v_mov_b32_e32 v34, v192
	v_mov_b32_e32 v35, v192
	v_readfirstlane_b32 s98, v0
	v_readfirstlane_b32 s99, v1
	v_readfirstlane_b32 s100, v184
	v_readfirstlane_b32 s101, v185
	v_mov_b32_e32 v211, 0
	v_mov_b32_e32 v213, 0
	s_nop 1
	v_subrev_u32_e32 v210, s98, v0
	v_subrev_u32_e32 v212, s100, v184
	s_nop 3
	s_add_u32 s98, s98, s76
	s_addc_u32 s99, s99, s77
	s_add_u32 s100, s100, s34
	s_addc_u32 s101, s101, s35
	v_subrev_u32_e32 v214, s76, v210
	v_add_u32_e32 v214, 0x10000, v214
	v_add_u32_e32 v215, s36, v212
	v_subrev_u32_e32 v215, s34, v215
.LBB0_731:
	s_mov_b32 s44, s29
	s_mov_b32 s28, s25
	v_add_u32_e32 v195, s45, v190
	ds_read_b64_tr_b16 v[196:197], v195 offset:24576
	ds_read_b64_tr_b16 v[198:199], v195 offset:25088
	v_add_f32_e32 v88, v68, v69
	v_add_f32_e32 v88, v70, v88
	v_add_f32_e32 v88, v71, v88
	v_add_f32_e32 v88, v72, v88
	v_add_f32_e32 v88, v73, v88
	v_cvt_pk_bf16_f32 v152, v68, v69
	v_cvt_pk_bf16_f32 v153, v70, v71
	v_mfma_f32_32x32x16_bf16 v[100:115], v[84:87], v[160:163], v[36:51]
	ds_read_b64_tr_b16 v[68:69], v195 offset:28672
	ds_read_b64_tr_b16 v[70:71], v195 offset:29184
	v_add_f32_e32 v84, v74, v88
	v_add_f32_e32 v84, v75, v84
	v_add_f32_e32 v84, v76, v84
	v_add_f32_e32 v132, v77, v84
	v_mfma_f32_32x32x16_bf16 v[84:99], v[168:171], v[160:163], v[36:51]
	v_cvt_pk_bf16_f32 v154, v72, v73
	v_cvt_pk_bf16_f32 v155, v74, v75
	ds_read_b64_tr_b16 v[72:73], v195 offset:25600
	ds_read_b64_tr_b16 v[74:75], v195 offset:26112
	v_add_f32_e32 v132, v78, v132
	v_add_f32_e32 v132, v79, v132
	v_add_f32_e32 v132, v80, v132
	v_add_f32_e32 v132, v81, v132
	v_cvt_pk_bf16_f32 v148, v76, v77
	v_cvt_pk_bf16_f32 v149, v78, v79
	v_mfma_f32_32x32x16_bf16 v[100:115], v[172:175], v[156:159], v[100:115]
	ds_read_b64_tr_b16 v[76:77], v195 offset:29696
	ds_read_b64_tr_b16 v[78:79], v195 offset:30208
	v_mfma_f32_32x32x16_bf16 v[84:99], v[164:167], v[156:159], v[84:99]
	v_add_f32_e32 v132, v82, v132
	v_add_f32_e32 v132, v83, v132
	v_add_f32_e32 v132, v52, v132
	v_add_f32_e32 v132, v53, v132
	v_cvt_pk_bf16_f32 v150, v80, v81
	v_cvt_pk_bf16_f32 v151, v82, v83
	ds_read_b64_tr_b16 v[80:81], v195 offset:26624
	ds_read_b64_tr_b16 v[82:83], v195 offset:27136
	v_mfma_f32_32x32x16_bf16 v[100:115], v[128:131], v[144:147], v[100:115]
	v_add_f32_e32 v128, v54, v132
	v_add_f32_e32 v128, v55, v128
	v_add_f32_e32 v128, v56, v128
	v_add_f32_e32 v128, v57, v128
	v_cvt_pk_bf16_f32 v140, v52, v53
	v_cvt_pk_bf16_f32 v141, v54, v55
	ds_read_b64_tr_b16 v[52:53], v195 offset:30720
	ds_read_b64_tr_b16 v[54:55], v195 offset:31232
	v_mfma_f32_32x32x16_bf16 v[84:99], v[124:127], v[144:147], v[84:99]
	v_add_f32_e32 v124, v58, v128
	v_add_f32_e32 v124, v59, v124
	v_add_f32_e32 v124, v60, v124
	v_add_f32_e32 v124, v61, v124
	v_cvt_pk_bf16_f32 v142, v56, v57
	v_cvt_pk_bf16_f32 v143, v58, v59
	ds_read_b64_tr_b16 v[56:57], v195 offset:27648
	ds_read_b64_tr_b16 v[58:59], v195 offset:28160
	v_mfma_f32_32x32x16_bf16 v[100:115], v[120:123], v[136:139], v[100:115]
	v_add_f32_e32 v120, v62, v124
	v_add_f32_e32 v120, v63, v120
	v_add_f32_e32 v120, v64, v120
	v_add_f32_e32 v120, v65, v120
	v_cvt_pk_bf16_f32 v132, v60, v61
	v_cvt_pk_bf16_f32 v133, v62, v63
	ds_read_b64_tr_b16 v[60:61], v195 offset:31744
	ds_read_b64_tr_b16 v[62:63], v195 offset:32256
	v_mfma_f32_32x32x16_bf16 v[84:99], v[116:119], v[136:139], v[84:99]
	v_add_f32_e32 v116, v66, v120
	v_add_f32_e32 v195, v67, v116
	v_cvt_pk_bf16_f32 v134, v64, v65
	v_cvt_pk_bf16_f32 v135, v66, v67
	s_add_i32 m0, s25, s59
	s_nop 0
	global_load_lds_dwordx4 v210, s[98:99]
	s_add_i32 m0, s44, s58
	s_nop 0
	global_load_lds_dwordx4 v212, s[100:101]
	s_waitcnt lgkmcnt(14)
	v_mfma_f32_32x32x16_bf16 v[4:19], v[152:155], v[196:199], v[4:19]
	v_exp_f32_e32 v100, v100
	v_exp_f32_e32 v101, v101
	v_exp_f32_e32 v102, v102
	v_exp_f32_e32 v103, v103
	s_waitcnt lgkmcnt(12)
	v_mfma_f32_32x32x16_bf16 v[20:35], v[152:155], v[68:71], v[20:35]
	v_exp_f32_e32 v104, v104
	v_exp_f32_e32 v105, v105
	v_exp_f32_e32 v106, v106
	v_exp_f32_e32 v107, v107
	v_add_u32_e32 v68, s44, v191
	ds_read_b128 v[64:67], v68
	ds_read_b128 v[120:123], v68 offset:512
	s_waitcnt lgkmcnt(12)
	v_mfma_f32_32x32x16_bf16 v[4:19], v[148:151], v[72:75], v[4:19]
	v_exp_f32_e32 v108, v108
	v_exp_f32_e32 v109, v109
	v_exp_f32_e32 v110, v110
	v_exp_f32_e32 v111, v111
	ds_read_b128 v[124:127], v68 offset:2048
	ds_read_b128 v[128:131], v68 offset:2560
	s_waitcnt lgkmcnt(12)
	v_mfma_f32_32x32x16_bf16 v[20:35], v[148:151], v[76:79], v[20:35]
	v_exp_f32_e32 v112, v112
	v_exp_f32_e32 v113, v113
	v_exp_f32_e32 v114, v114
	v_exp_f32_e32 v115, v115
	ds_read_b128 v[164:167], v68 offset:4096
	ds_read_b128 v[168:171], v68 offset:4608
	s_waitcnt lgkmcnt(12)
	v_mfma_f32_32x32x16_bf16 v[4:19], v[140:143], v[80:83], v[4:19]
	v_exp_f32_e32 v84, v84
	v_exp_f32_e32 v85, v85
	v_exp_f32_e32 v86, v86
	v_exp_f32_e32 v87, v87
	ds_read_b128 v[172:175], v68 offset:6144
	ds_read_b128 v[116:119], v68 offset:6656
	s_waitcnt lgkmcnt(12)
	v_mfma_f32_32x32x16_bf16 v[20:35], v[140:143], v[52:55], v[20:35]
	v_exp_f32_e32 v88, v88
	v_exp_f32_e32 v89, v89
	v_exp_f32_e32 v90, v90
	v_exp_f32_e32 v91, v91
	s_waitcnt lgkmcnt(10)
	v_mfma_f32_32x32x16_bf16 v[4:19], v[132:135], v[56:59], v[4:19]
	v_exp_f32_e32 v92, v92
	v_exp_f32_e32 v93, v93
	v_exp_f32_e32 v94, v94
	v_exp_f32_e32 v95, v95
	s_waitcnt lgkmcnt(8)
	v_mfma_f32_32x32x16_bf16 v[20:35], v[132:135], v[60:63], v[20:35]
	v_exp_f32_e32 v96, v96
	v_exp_f32_e32 v97, v97
	v_exp_f32_e32 v98, v98
	v_exp_f32_e32 v99, v99
	s_waitcnt vmcnt(2) lgkmcnt(0)
	s_barrier
	s_add_i32 s25, s44, 0x2000
	s_cmpk_lg_i32 s44, 0x4000
	s_cselect_b32 s25, s25, 0
	v_add_u32_e32 v200, s28, v190
	ds_read_b64_tr_b16 v[196:197], v200 offset:24576
	ds_read_b64_tr_b16 v[198:199], v200 offset:25088
	v_mfma_f32_32x32x16_bf16 v[68:83], v[64:67], v[160:163], v[36:51]
	v_add_f32_e32 v52, v100, v101
	v_add_f32_e32 v52, v102, v52
	v_add_f32_e32 v52, v103, v52
	v_add_f32_e32 v52, v104, v52
	v_add_f32_e32 v52, v105, v52
	v_cvt_pk_bf16_f32 v152, v100, v101
	v_cvt_pk_bf16_f32 v153, v102, v103
	ds_read_b64_tr_b16 v[100:101], v200 offset:28672
	ds_read_b64_tr_b16 v[102:103], v200 offset:29184
	v_add_f32_e32 v52, v106, v52
	v_add_f32_e32 v52, v107, v52
	v_add_f32_e32 v52, v108, v52
	v_add_f32_e32 v132, v109, v52
	v_mfma_f32_32x32x16_bf16 v[52:67], v[120:123], v[160:163], v[36:51]
	v_cvt_pk_bf16_f32 v154, v104, v105
	v_cvt_pk_bf16_f32 v155, v106, v107
	ds_read_b64_tr_b16 v[104:105], v200 offset:25600
	ds_read_b64_tr_b16 v[106:107], v200 offset:26112
	v_mfma_f32_32x32x16_bf16 v[68:83], v[124:127], v[156:159], v[68:83]
	v_add_f32_e32 v120, v110, v132
	v_add_f32_e32 v120, v111, v120
	v_add_f32_e32 v120, v112, v120
	v_add_f32_e32 v120, v113, v120
	v_cvt_pk_bf16_f32 v148, v108, v109
	v_cvt_pk_bf16_f32 v149, v110, v111
	ds_read_b64_tr_b16 v[108:109], v200 offset:29696
	ds_read_b64_tr_b16 v[110:111], v200 offset:30208
	v_mfma_f32_32x32x16_bf16 v[52:67], v[128:131], v[156:159], v[52:67]
	v_add_f32_e32 v120, v114, v120
	v_add_f32_e32 v120, v115, v120
	v_add_f32_e32 v120, v84, v120
	v_add_f32_e32 v120, v85, v120
	v_cvt_pk_bf16_f32 v150, v112, v113
	v_cvt_pk_bf16_f32 v151, v114, v115
	ds_read_b64_tr_b16 v[112:113], v200 offset:26624
	ds_read_b64_tr_b16 v[114:115], v200 offset:27136
	v_mfma_f32_32x32x16_bf16 v[68:83], v[164:167], v[144:147], v[68:83]
	v_add_f32_e32 v120, v86, v120
	v_add_f32_e32 v120, v87, v120
	v_add_f32_e32 v120, v88, v120
	v_add_f32_e32 v120, v89, v120
	v_cvt_pk_bf16_f32 v140, v84, v85
	v_cvt_pk_bf16_f32 v141, v86, v87
	ds_read_b64_tr_b16 v[206:207], v200 offset:30720
	ds_read_b64_tr_b16 v[208:209], v200 offset:31232
	v_mfma_f32_32x32x16_bf16 v[52:67], v[168:171], v[144:147], v[52:67]
	v_add_f32_e32 v84, v90, v120
	v_add_f32_e32 v84, v91, v84
	v_add_f32_e32 v84, v92, v84
	v_add_f32_e32 v84, v93, v84
	v_cvt_pk_bf16_f32 v142, v88, v89
	v_cvt_pk_bf16_f32 v143, v90, v91
	ds_read_b64_tr_b16 v[88:89], v200 offset:27648
	ds_read_b64_tr_b16 v[90:91], v200 offset:28160
	v_mfma_f32_32x32x16_bf16 v[68:83], v[172:175], v[136:139], v[68:83]
	v_add_f32_e32 v84, v94, v84
	v_add_f32_e32 v84, v95, v84
	v_add_f32_e32 v84, v96, v84
	v_add_f32_e32 v84, v97, v84
	v_cvt_pk_bf16_f32 v132, v92, v93
	v_cvt_pk_bf16_f32 v133, v94, v95
	ds_read_b64_tr_b16 v[92:93], v200 offset:31744
	ds_read_b64_tr_b16 v[94:95], v200 offset:32256
	v_mfma_f32_32x32x16_bf16 v[52:67], v[116:119], v[136:139], v[52:67]
	v_add_f32_e32 v84, v98, v84
	v_add_f32_e32 v200, v99, v84
	v_cvt_pk_bf16_f32 v134, v96, v97
	v_cvt_pk_bf16_f32 v135, v98, v99
	s_add_i32 m0, s44, s59
	s_nop 0
	global_load_lds_dwordx4 v214, s[98:99]
	s_add_i32 m0, s25, s58
	s_nop 0
	global_load_lds_dwordx4 v215, s[100:101]
	s_add_u32 s98, s98, s36
	s_addc_u32 s99, s99, s37
	s_add_u32 s100, s100, s36
	s_addc_u32 s101, s101, s37
	s_waitcnt lgkmcnt(14)
	v_mfma_f32_32x32x16_bf16 v[4:19], v[152:155], v[196:199], v[4:19]
	v_exp_f32_e32 v68, v68
	v_exp_f32_e32 v69, v69
	v_exp_f32_e32 v70, v70
	v_exp_f32_e32 v71, v71
	s_waitcnt lgkmcnt(12)
	v_mfma_f32_32x32x16_bf16 v[20:35], v[152:155], v[100:103], v[20:35]
	v_exp_f32_e32 v72, v72
	v_exp_f32_e32 v73, v73
	v_exp_f32_e32 v74, v74
	v_exp_f32_e32 v75, v75
	v_add_u32_e32 v96, s25, v191
	ds_read_b128 v[84:87], v96
	ds_read_b128 v[168:171], v96 offset:512
	s_waitcnt lgkmcnt(12)
	v_mfma_f32_32x32x16_bf16 v[4:19], v[148:151], v[104:107], v[4:19]
	v_exp_f32_e32 v76, v76
	v_exp_f32_e32 v77, v77
	v_exp_f32_e32 v78, v78
	v_exp_f32_e32 v79, v79
	ds_read_b128 v[172:175], v96 offset:2048
	ds_read_b128 v[164:167], v96 offset:2560
	s_waitcnt lgkmcnt(12)
	v_mfma_f32_32x32x16_bf16 v[20:35], v[148:151], v[108:111], v[20:35]
	v_exp_f32_e32 v80, v80
	v_exp_f32_e32 v81, v81
	v_exp_f32_e32 v82, v82
	v_exp_f32_e32 v83, v83
	ds_read_b128 v[128:131], v96 offset:4096
	ds_read_b128 v[124:127], v96 offset:4608
	s_waitcnt lgkmcnt(12)
	v_mfma_f32_32x32x16_bf16 v[4:19], v[140:143], v[112:115], v[4:19]
	v_exp_f32_e32 v52, v52
	v_exp_f32_e32 v53, v53
	v_exp_f32_e32 v54, v54
	v_exp_f32_e32 v55, v55
	ds_read_b128 v[120:123], v96 offset:6144
	ds_read_b128 v[116:119], v96 offset:6656
	s_waitcnt lgkmcnt(12)
	v_mfma_f32_32x32x16_bf16 v[20:35], v[140:143], v[206:209], v[20:35]
	v_exp_f32_e32 v56, v56
	v_exp_f32_e32 v57, v57
	v_exp_f32_e32 v58, v58
	v_exp_f32_e32 v59, v59
	s_waitcnt lgkmcnt(10)
	v_mfma_f32_32x32x16_bf16 v[4:19], v[132:135], v[88:91], v[4:19]
	v_exp_f32_e32 v60, v60
	v_exp_f32_e32 v61, v61
	v_exp_f32_e32 v62, v62
	v_exp_f32_e32 v63, v63
	s_waitcnt lgkmcnt(8)
	v_mfma_f32_32x32x16_bf16 v[20:35], v[132:135], v[92:95], v[20:35]
	v_exp_f32_e32 v64, v64
	v_exp_f32_e32 v65, v65
	v_exp_f32_e32 v66, v66
	v_exp_f32_e32 v67, v67
	s_add_i32 s28, s25, 0x2000
	s_waitcnt vmcnt(2) lgkmcnt(0)
	s_barrier
	s_cmpk_lg_i32 s25, 0x4000
	v_add_f32_e32 v88, v192, v195
	s_cselect_b32 s29, s28, 0
	s_add_i32 s24, s24, 2
	v_add_f32_e32 v192, v88, v200
	s_cmpk_gt_u32 s24, 0xf8
	s_mov_b32 s45, s44
	s_cbranch_scc0 .LBB0_731
	s_sub_u32 s98, s98, s76
	s_subb_u32 s99, s99, s77
	s_sub_u32 s100, s100, s34
	s_subb_u32 s101, s101, s35
	v_lshl_add_u64 v[0:1], s[98:99], 0, v[210:211]
	v_lshl_add_u64 v[184:185], s[100:101], 0, v[212:213]
	s_and_b32 s24, s60, 0x3fffffc0
	s_cmp_lg_u32 0, -1
	s_cselect_b32 s28, 0, 0
	s_addk_i32 s28, 0x6000
	s_lshl_b32 s24, s24, 2
	v_add3_u32 v0, v194, s28, v193
	s_add_i32 s28, s24, 0
	v_add_u32_e32 v1, s44, v190
	ds_read_b64_tr_b16 v[194:195], v1 offset:24576
	ds_read_b64_tr_b16 v[196:197], v1 offset:25088
	v_add_f32_e32 v88, v68, v69
	v_add_f32_e32 v88, v70, v88
	v_add_f32_e32 v88, v71, v88
	v_add_f32_e32 v88, v72, v88
	v_add_f32_e32 v88, v73, v88
	v_cvt_pk_bf16_f32 v152, v68, v69
	v_cvt_pk_bf16_f32 v153, v70, v71
	s_waitcnt lgkmcnt(9)
	v_mfma_f32_32x32x16_bf16 v[100:115], v[84:87], v[160:163], v[36:51]
	ds_read_b64_tr_b16 v[68:69], v1 offset:28672
	ds_read_b64_tr_b16 v[70:71], v1 offset:29184
	v_add_f32_e32 v84, v74, v88
	v_add_f32_e32 v84, v75, v84
	v_add_f32_e32 v84, v76, v84
	v_add_f32_e32 v132, v77, v84
	v_cvt_pk_bf16_f32 v154, v72, v73
	v_cvt_pk_bf16_f32 v155, v74, v75
	s_waitcnt lgkmcnt(10)
	v_mfma_f32_32x32x16_bf16 v[84:99], v[168:171], v[160:163], v[36:51]
	ds_read_b64_tr_b16 v[72:73], v1 offset:25600
	ds_read_b64_tr_b16 v[74:75], v1 offset:26112
	v_add_f32_e32 v132, v78, v132
	v_add_f32_e32 v132, v79, v132
	v_add_f32_e32 v132, v80, v132
	v_add_f32_e32 v132, v81, v132
	v_cvt_pk_bf16_f32 v148, v76, v77
	v_cvt_pk_bf16_f32 v149, v78, v79
	s_waitcnt lgkmcnt(11)
	v_mfma_f32_32x32x16_bf16 v[100:115], v[172:175], v[156:159], v[100:115]
	ds_read_b64_tr_b16 v[76:77], v1 offset:29696
	ds_read_b64_tr_b16 v[78:79], v1 offset:30208
	v_add_f32_e32 v132, v82, v132
	v_add_f32_e32 v132, v83, v132
	v_add_f32_e32 v132, v52, v132
	v_add_f32_e32 v132, v53, v132
	v_cvt_pk_bf16_f32 v150, v80, v81
	v_cvt_pk_bf16_f32 v151, v82, v83
	s_waitcnt lgkmcnt(12)
	v_mfma_f32_32x32x16_bf16 v[84:99], v[164:167], v[156:159], v[84:99]
	ds_read_b64_tr_b16 v[80:81], v1 offset:26624
	ds_read_b64_tr_b16 v[82:83], v1 offset:27136
	s_waitcnt lgkmcnt(13)
	v_mfma_f32_32x32x16_bf16 v[100:115], v[128:131], v[144:147], v[100:115]
	v_add_f32_e32 v128, v54, v132
	v_add_f32_e32 v128, v55, v128
	v_add_f32_e32 v128, v56, v128
	v_add_f32_e32 v128, v57, v128
	v_cvt_pk_bf16_f32 v140, v52, v53
	v_cvt_pk_bf16_f32 v141, v54, v55
	ds_read_b64_tr_b16 v[52:53], v1 offset:30720
	ds_read_b64_tr_b16 v[54:55], v1 offset:31232
	s_waitcnt lgkmcnt(14)
	v_mfma_f32_32x32x16_bf16 v[84:99], v[124:127], v[144:147], v[84:99]
	v_add_f32_e32 v124, v58, v128
	v_add_f32_e32 v124, v59, v124
	v_add_f32_e32 v124, v60, v124
	v_add_f32_e32 v124, v61, v124
	v_cvt_pk_bf16_f32 v142, v56, v57
	v_cvt_pk_bf16_f32 v143, v58, v59
	ds_read_b64_tr_b16 v[56:57], v1 offset:27648
	ds_read_b64_tr_b16 v[58:59], v1 offset:28160
	s_waitcnt lgkmcnt(14)
	v_mfma_f32_32x32x16_bf16 v[100:115], v[120:123], v[136:139], v[100:115]
	v_add_f32_e32 v120, v62, v124
	v_add_f32_e32 v120, v63, v120
	v_add_f32_e32 v120, v64, v120
	v_add_f32_e32 v120, v65, v120
	v_cvt_pk_bf16_f32 v132, v60, v61
	v_cvt_pk_bf16_f32 v133, v62, v63
	ds_read_b64_tr_b16 v[60:61], v1 offset:31744
	ds_read_b64_tr_b16 v[62:63], v1 offset:32256
	v_add_f32_e32 v1, v66, v120
	v_add_f32_e32 v1, v67, v1
	v_add_f32_e32 v1, 0, v1
	v_cvt_pk_bf16_f32 v134, v64, v65
	v_cvt_pk_bf16_f32 v135, v66, v67
	v_mfma_f32_32x32x16_bf16 v[84:99], v[116:119], v[136:139], v[84:99]
	s_mov_b64 s[46:47], 0x3f8000
	s_add_i32 s24, s25, s59
	v_lshl_add_u64 v[64:65], v[182:183], 0, s[46:47]
	s_mov_b32 s44, m0
	s_mov_b32 m0, s24
	s_nop 0
	global_load_lds_dwordx4 v[64:65], off
	s_mov_b32 m0, s44
	s_mov_b64 s[44:45], 0x3f0000
	v_lshl_add_u64 v[64:65], v[180:181], 0, s[44:45]
	s_add_i32 s24, s29, s58
	s_mov_b32 s44, m0
	s_mov_b32 m0, s24
	s_nop 0
	global_load_lds_dwordx4 v[64:65], off
	s_mov_b32 m0, s44
	v_add_f32_e32 v1, v192, v1
	s_waitcnt lgkmcnt(14)
	v_mfma_f32_32x32x16_bf16 v[4:19], v[152:155], v[194:197], v[4:19]
	v_exp_f32_e32 v100, v100
	v_exp_f32_e32 v101, v101
	v_exp_f32_e32 v102, v102
	v_exp_f32_e32 v103, v103
	s_waitcnt lgkmcnt(12)
	v_mfma_f32_32x32x16_bf16 v[20:35], v[152:155], v[68:71], v[20:35]
	v_exp_f32_e32 v104, v104
	v_exp_f32_e32 v105, v105
	v_exp_f32_e32 v106, v106
	v_exp_f32_e32 v107, v107
	v_add_u32_e32 v68, s29, v191
	ds_read_b128 v[64:67], v68
	ds_read_b128 v[164:167], v68 offset:512
	s_waitcnt lgkmcnt(12)
	v_mfma_f32_32x32x16_bf16 v[4:19], v[148:151], v[72:75], v[4:19]
	v_exp_f32_e32 v108, v108
	v_exp_f32_e32 v109, v109
	v_exp_f32_e32 v110, v110
	v_exp_f32_e32 v111, v111
	ds_read_b128 v[72:75], v68 offset:2048
	ds_read_b128 v[168:171], v68 offset:2560
	s_waitcnt lgkmcnt(12)
	v_mfma_f32_32x32x16_bf16 v[20:35], v[148:151], v[76:79], v[20:35]
	v_exp_f32_e32 v112, v112
	v_exp_f32_e32 v113, v113
	v_exp_f32_e32 v114, v114
	v_exp_f32_e32 v115, v115
	ds_read_b128 v[76:79], v68 offset:4096
	ds_read_b128 v[172:175], v68 offset:4608
	s_waitcnt lgkmcnt(12)
	v_mfma_f32_32x32x16_bf16 v[4:19], v[140:143], v[80:83], v[4:19]
	v_exp_f32_e32 v84, v84
	v_exp_f32_e32 v85, v85
	v_exp_f32_e32 v86, v86
	v_exp_f32_e32 v87, v87
	ds_read_b128 v[80:83], v68 offset:6144
	ds_read_b128 v[68:71], v68 offset:6656
	s_waitcnt lgkmcnt(12)
	v_mfma_f32_32x32x16_bf16 v[20:35], v[140:143], v[52:55], v[20:35]
	v_exp_f32_e32 v88, v88
	v_exp_f32_e32 v89, v89
	v_exp_f32_e32 v90, v90
	v_exp_f32_e32 v91, v91
	s_waitcnt lgkmcnt(10)
	v_mfma_f32_32x32x16_bf16 v[4:19], v[132:135], v[56:59], v[4:19]
	v_exp_f32_e32 v92, v92
	v_exp_f32_e32 v93, v93
	v_exp_f32_e32 v94, v94
	v_exp_f32_e32 v95, v95
	s_waitcnt lgkmcnt(8)
	v_mfma_f32_32x32x16_bf16 v[20:35], v[132:135], v[60:63], v[20:35]
	v_exp_f32_e32 v96, v96
	v_exp_f32_e32 v97, v97
	v_exp_f32_e32 v98, v98
	v_exp_f32_e32 v99, v99
	s_waitcnt vmcnt(2) lgkmcnt(0)
	s_barrier
	s_add_i32 s24, s29, 0x2000
	s_cmpk_lg_i32 s29, 0x4000
	s_cselect_b32 s44, s24, 0
	v_add_u32_e32 v184, s25, v190
	ds_read_b64_tr_b16 v[192:193], v184 offset:24576
	ds_read_b64_tr_b16 v[194:195], v184 offset:25088
	v_add_f32_e32 v52, v100, v101
	v_add_f32_e32 v52, v102, v52
	v_add_f32_e32 v52, v103, v52
	v_add_f32_e32 v52, v104, v52
	v_add_f32_e32 v52, v105, v52
	v_cvt_pk_bf16_f32 v152, v100, v101
	v_cvt_pk_bf16_f32 v153, v102, v103
	s_waitcnt lgkmcnt(9)
	v_mfma_f32_32x32x16_bf16 v[116:131], v[64:67], v[160:163], v[36:51]
	ds_read_b64_tr_b16 v[100:101], v184 offset:28672
	ds_read_b64_tr_b16 v[102:103], v184 offset:29184
	v_add_f32_e32 v52, v106, v52
	v_add_f32_e32 v52, v107, v52
	v_add_f32_e32 v52, v108, v52
	v_add_f32_e32 v132, v109, v52
	v_cvt_pk_bf16_f32 v154, v104, v105
	v_cvt_pk_bf16_f32 v155, v106, v107
	s_waitcnt lgkmcnt(10)
	v_mfma_f32_32x32x16_bf16 v[52:67], v[164:167], v[160:163], v[36:51]
	ds_read_b64_tr_b16 v[104:105], v184 offset:25600
	ds_read_b64_tr_b16 v[106:107], v184 offset:26112
	s_waitcnt lgkmcnt(11)
	v_mfma_f32_32x32x16_bf16 v[116:131], v[72:75], v[156:159], v[116:131]
	v_add_f32_e32 v72, v110, v132
	v_add_f32_e32 v72, v111, v72
	v_add_f32_e32 v72, v112, v72
	v_add_f32_e32 v132, v113, v72
	v_cvt_pk_bf16_f32 v148, v108, v109
	v_cvt_pk_bf16_f32 v149, v110, v111
	ds_read_b64_tr_b16 v[72:73], v184 offset:29696
	ds_read_b64_tr_b16 v[74:75], v184 offset:30208
	v_add_f32_e32 v108, v114, v132
	v_add_f32_e32 v108, v115, v108
	v_add_f32_e32 v108, v84, v108
	v_add_f32_e32 v132, v85, v108
	v_cvt_pk_bf16_f32 v150, v112, v113
	v_cvt_pk_bf16_f32 v151, v114, v115
	s_waitcnt lgkmcnt(12)
	v_mfma_f32_32x32x16_bf16 v[52:67], v[168:171], v[156:159], v[52:67]
	ds_read_b64_tr_b16 v[108:109], v184 offset:26624
	ds_read_b64_tr_b16 v[110:111], v184 offset:27136
	s_waitcnt lgkmcnt(13)
	v_mfma_f32_32x32x16_bf16 v[116:131], v[76:79], v[144:147], v[116:131]
	v_add_f32_e32 v76, v86, v132
	v_add_f32_e32 v76, v87, v76
	v_add_f32_e32 v76, v88, v76
	v_add_f32_e32 v112, v89, v76
	v_cvt_pk_bf16_f32 v140, v84, v85
	v_cvt_pk_bf16_f32 v141, v86, v87
	ds_read_b64_tr_b16 v[76:77], v184 offset:30720
	ds_read_b64_tr_b16 v[78:79], v184 offset:31232
	v_add_f32_e32 v84, v90, v112
	v_add_f32_e32 v84, v91, v84
	v_add_f32_e32 v84, v92, v84
	v_add_f32_e32 v84, v93, v84
	v_cvt_pk_bf16_f32 v142, v88, v89
	v_cvt_pk_bf16_f32 v143, v90, v91
	s_waitcnt lgkmcnt(14)
	v_mfma_f32_32x32x16_bf16 v[52:67], v[172:175], v[144:147], v[52:67]
	ds_read_b64_tr_b16 v[88:89], v184 offset:27648
	ds_read_b64_tr_b16 v[90:91], v184 offset:28160
	s_waitcnt lgkmcnt(14)
	v_mfma_f32_32x32x16_bf16 v[116:131], v[80:83], v[136:139], v[116:131]
	v_add_f32_e32 v80, v94, v84
	v_add_f32_e32 v80, v95, v80
	v_add_f32_e32 v80, v96, v80
	v_add_f32_e32 v84, v97, v80
	v_cvt_pk_bf16_f32 v132, v92, v93
	v_cvt_pk_bf16_f32 v133, v94, v95
	ds_read_b64_tr_b16 v[80:81], v184 offset:31744
	ds_read_b64_tr_b16 v[82:83], v184 offset:32256
	v_mfma_f32_32x32x16_bf16 v[52:67], v[68:71], v[136:139], v[52:67]
	v_add_f32_e32 v68, v98, v84
	v_add_f32_e32 v68, v99, v68
	v_add_f32_e32 v68, 0, v68
	v_cvt_pk_bf16_f32 v134, v96, v97
	v_cvt_pk_bf16_f32 v135, v98, v99
	s_mov_b64 s[60:61], 0x3fc000
	v_add_f32_e32 v1, v1, v68
	s_add_i32 s24, s29, s59
	v_lshl_add_u64 v[68:69], v[182:183], 0, s[60:61]
	s_mov_b32 s25, m0
	s_mov_b32 m0, s24
	s_nop 0
	global_load_lds_dwordx4 v[68:69], off
	s_mov_b32 m0, s25
	s_mov_b64 s[24:25], 0x3f4000
	s_add_i32 s45, s44, s58
	v_lshl_add_u64 v[68:69], v[180:181], 0, s[24:25]
	s_mov_b32 s24, m0
	s_mov_b32 m0, s45
	s_nop 0
	global_load_lds_dwordx4 v[68:69], off
	s_mov_b32 m0, s24
	s_waitcnt lgkmcnt(14)
	v_mfma_f32_32x32x16_bf16 v[4:19], v[152:155], v[192:195], v[4:19]
	v_exp_f32_e32 v116, v116
	v_exp_f32_e32 v117, v117
	v_exp_f32_e32 v118, v118
	v_exp_f32_e32 v119, v119
	s_waitcnt lgkmcnt(12)
	v_mfma_f32_32x32x16_bf16 v[20:35], v[152:155], v[100:103], v[20:35]
	v_exp_f32_e32 v120, v120
	v_exp_f32_e32 v121, v121
	v_exp_f32_e32 v122, v122
	v_exp_f32_e32 v123, v123
	v_add_u32_e32 v84, s44, v191
	ds_read_b128 v[68:71], v84
	ds_read_b128 v[92:95], v84 offset:512
	s_waitcnt lgkmcnt(12)
	v_mfma_f32_32x32x16_bf16 v[4:19], v[148:151], v[104:107], v[4:19]
	v_exp_f32_e32 v124, v124
	v_exp_f32_e32 v125, v125
	v_exp_f32_e32 v126, v126
	v_exp_f32_e32 v127, v127
	ds_read_b128 v[96:99], v84 offset:2048
	ds_read_b128 v[164:167], v84 offset:2560
	s_waitcnt lgkmcnt(12)
	v_mfma_f32_32x32x16_bf16 v[20:35], v[148:151], v[72:75], v[20:35]
	v_exp_f32_e32 v128, v128
	v_exp_f32_e32 v129, v129
	v_exp_f32_e32 v130, v130
	v_exp_f32_e32 v131, v131
	ds_read_b128 v[168:171], v84 offset:4096
	ds_read_b128 v[172:175], v84 offset:4608
	s_waitcnt lgkmcnt(12)
	v_mfma_f32_32x32x16_bf16 v[4:19], v[140:143], v[108:111], v[4:19]
	v_exp_f32_e32 v52, v52
	v_exp_f32_e32 v53, v53
	v_exp_f32_e32 v54, v54
	v_exp_f32_e32 v55, v55
	ds_read_b128 v[182:185], v84 offset:6144
	ds_read_b128 v[84:87], v84 offset:6656
	s_waitcnt lgkmcnt(12)
	v_mfma_f32_32x32x16_bf16 v[20:35], v[140:143], v[76:79], v[20:35]
	v_exp_f32_e32 v56, v56
	v_exp_f32_e32 v57, v57
	v_exp_f32_e32 v58, v58
	v_exp_f32_e32 v59, v59
	s_waitcnt lgkmcnt(10)
	v_mfma_f32_32x32x16_bf16 v[4:19], v[132:135], v[88:91], v[4:19]
	v_exp_f32_e32 v60, v60
	v_exp_f32_e32 v61, v61
	v_exp_f32_e32 v62, v62
	v_exp_f32_e32 v63, v63
	s_waitcnt lgkmcnt(8)
	v_mfma_f32_32x32x16_bf16 v[20:35], v[132:135], v[80:83], v[20:35]
	v_exp_f32_e32 v64, v64
	v_exp_f32_e32 v65, v65
	v_exp_f32_e32 v66, v66
	v_exp_f32_e32 v67, v67
	s_waitcnt vmcnt(2) lgkmcnt(0)
	s_barrier
	s_add_i32 s24, s44, 0x2000
	s_cmpk_lg_i32 s44, 0x4000
	s_cselect_b32 s25, s24, 0
	v_add_u32_e32 v192, s29, v190
	ds_read_b64_tr_b16 v[88:89], v192 offset:24576
	ds_read_b64_tr_b16 v[90:91], v192 offset:25088
	v_add_f32_e32 v72, v116, v117
	v_add_f32_e32 v72, v118, v72
	v_add_f32_e32 v72, v119, v72
	v_add_f32_e32 v72, v120, v72
	v_add_f32_e32 v72, v121, v72
	v_cvt_pk_bf16_f32 v152, v116, v117
	v_cvt_pk_bf16_f32 v153, v118, v119
	s_waitcnt lgkmcnt(9)
	v_mfma_f32_32x32x16_bf16 v[100:115], v[68:71], v[160:163], v[36:51]
	ds_read_b64_tr_b16 v[116:117], v192 offset:28672
	ds_read_b64_tr_b16 v[118:119], v192 offset:29184
	v_add_f32_e32 v68, v122, v72
	v_add_f32_e32 v68, v123, v68
	v_add_f32_e32 v68, v124, v68
	v_add_f32_e32 v132, v125, v68
	v_cvt_pk_bf16_f32 v154, v120, v121
	v_cvt_pk_bf16_f32 v155, v122, v123
	s_waitcnt lgkmcnt(10)
	v_mfma_f32_32x32x16_bf16 v[68:83], v[92:95], v[160:163], v[36:51]
	ds_read_b64_tr_b16 v[92:93], v192 offset:25600
	ds_read_b64_tr_b16 v[94:95], v192 offset:26112
	s_waitcnt lgkmcnt(11)
	v_mfma_f32_32x32x16_bf16 v[100:115], v[96:99], v[156:159], v[100:115]
	v_add_f32_e32 v96, v126, v132
	v_add_f32_e32 v96, v127, v96
	v_add_f32_e32 v96, v128, v96
	v_add_f32_e32 v120, v129, v96
	v_cvt_pk_bf16_f32 v148, v124, v125
	v_cvt_pk_bf16_f32 v149, v126, v127
	ds_read_b64_tr_b16 v[96:97], v192 offset:29696
	ds_read_b64_tr_b16 v[98:99], v192 offset:30208
	v_add_f32_e32 v120, v130, v120
	v_add_f32_e32 v120, v131, v120
	v_add_f32_e32 v120, v52, v120
	v_add_f32_e32 v124, v53, v120
	v_cvt_pk_bf16_f32 v150, v128, v129
	v_cvt_pk_bf16_f32 v151, v130, v131
	s_waitcnt lgkmcnt(12)
	v_mfma_f32_32x32x16_bf16 v[68:83], v[164:167], v[156:159], v[68:83]
	ds_read_b64_tr_b16 v[120:121], v192 offset:26624
	ds_read_b64_tr_b16 v[122:123], v192 offset:27136
	v_add_f32_e32 v124, v54, v124
	v_add_f32_e32 v124, v55, v124
	v_add_f32_e32 v124, v56, v124
	v_add_f32_e32 v124, v57, v124
	v_cvt_pk_bf16_f32 v140, v52, v53
	v_cvt_pk_bf16_f32 v141, v54, v55
	s_waitcnt lgkmcnt(13)
	v_mfma_f32_32x32x16_bf16 v[100:115], v[168:171], v[144:147], v[100:115]
	ds_read_b64_tr_b16 v[52:53], v192 offset:30720
	ds_read_b64_tr_b16 v[54:55], v192 offset:31232
	v_add_f32_e32 v124, v58, v124
	v_add_f32_e32 v124, v59, v124
	v_add_f32_e32 v124, v60, v124
	v_add_f32_e32 v124, v61, v124
	v_cvt_pk_bf16_f32 v142, v56, v57
	v_cvt_pk_bf16_f32 v143, v58, v59
	s_waitcnt lgkmcnt(14)
	v_mfma_f32_32x32x16_bf16 v[68:83], v[172:175], v[144:147], v[68:83]
	ds_read_b64_tr_b16 v[56:57], v192 offset:27648
	ds_read_b64_tr_b16 v[58:59], v192 offset:28160
	v_add_f32_e32 v124, v62, v124
	v_add_f32_e32 v124, v63, v124
	v_add_f32_e32 v124, v64, v124
	v_add_f32_e32 v124, v65, v124
	v_cvt_pk_bf16_f32 v132, v60, v61
	v_cvt_pk_bf16_f32 v133, v62, v63
	s_waitcnt lgkmcnt(14)
	v_mfma_f32_32x32x16_bf16 v[100:115], v[182:185], v[136:139], v[100:115]
	ds_read_b64_tr_b16 v[60:61], v192 offset:31744
	ds_read_b64_tr_b16 v[62:63], v192 offset:32256
	v_mfma_f32_32x32x16_bf16 v[68:83], v[84:87], v[136:139], v[68:83]
	v_add_f32_e32 v84, v66, v124
	v_add_f32_e32 v84, v67, v84
	v_add_f32_e32 v84, 0, v84
	v_cvt_pk_bf16_f32 v134, v64, v65
	v_cvt_pk_bf16_f32 v135, v66, v67
	v_lshl_add_u64 v[64:65], v[180:181], 0, s[46:47]
	s_add_i32 s24, s25, s58
	s_mov_b32 s29, m0
	s_mov_b32 m0, s24
	s_nop 0
	global_load_lds_dwordx4 v[64:65], off
	s_mov_b32 m0, s29
	v_add_f32_e32 v1, v1, v84
	s_waitcnt lgkmcnt(14)
	v_mfma_f32_32x32x16_bf16 v[4:19], v[152:155], v[88:91], v[4:19]
	v_exp_f32_e32 v100, v100
	v_exp_f32_e32 v101, v101
	v_exp_f32_e32 v102, v102
	v_exp_f32_e32 v103, v103
	s_waitcnt lgkmcnt(12)
	v_mfma_f32_32x32x16_bf16 v[20:35], v[152:155], v[116:119], v[20:35]
	v_exp_f32_e32 v104, v104
	v_exp_f32_e32 v105, v105
	v_exp_f32_e32 v106, v106
	v_exp_f32_e32 v107, v107
	v_add_u32_e32 v84, s25, v191
	ds_read_b128 v[64:67], v84
	ds_read_b128 v[124:127], v84 offset:512
	s_waitcnt lgkmcnt(12)
	v_mfma_f32_32x32x16_bf16 v[4:19], v[148:151], v[92:95], v[4:19]
	v_exp_f32_e32 v108, v108
	v_exp_f32_e32 v109, v109
	v_exp_f32_e32 v110, v110
	v_exp_f32_e32 v111, v111
	ds_read_b128 v[128:131], v84 offset:2048
	ds_read_b128 v[164:167], v84 offset:2560
	s_waitcnt lgkmcnt(12)
	v_mfma_f32_32x32x16_bf16 v[20:35], v[148:151], v[96:99], v[20:35]
	v_exp_f32_e32 v112, v112
	v_exp_f32_e32 v113, v113
	v_exp_f32_e32 v114, v114
	v_exp_f32_e32 v115, v115
	ds_read_b128 v[168:171], v84 offset:4096
	ds_read_b128 v[172:175], v84 offset:4608
	s_waitcnt lgkmcnt(12)
	v_mfma_f32_32x32x16_bf16 v[4:19], v[140:143], v[120:123], v[4:19]
	v_exp_f32_e32 v68, v68
	v_exp_f32_e32 v69, v69
	v_exp_f32_e32 v70, v70
	v_exp_f32_e32 v71, v71
	ds_read_b128 v[120:123], v84 offset:6144
	ds_read_b128 v[116:119], v84 offset:6656
	s_waitcnt lgkmcnt(12)
	v_mfma_f32_32x32x16_bf16 v[20:35], v[140:143], v[52:55], v[20:35]
	v_exp_f32_e32 v72, v72
	v_exp_f32_e32 v73, v73
	v_exp_f32_e32 v74, v74
	v_exp_f32_e32 v75, v75
	s_waitcnt lgkmcnt(10)
	v_mfma_f32_32x32x16_bf16 v[4:19], v[132:135], v[56:59], v[4:19]
	v_exp_f32_e32 v76, v76
	v_exp_f32_e32 v77, v77
	v_exp_f32_e32 v78, v78
	v_exp_f32_e32 v79, v79
	s_waitcnt lgkmcnt(8)
	v_mfma_f32_32x32x16_bf16 v[20:35], v[132:135], v[60:63], v[20:35]
	v_exp_f32_e32 v80, v80
	v_exp_f32_e32 v81, v81
	v_exp_f32_e32 v82, v82
	v_exp_f32_e32 v83, v83
	s_waitcnt vmcnt(1) lgkmcnt(0)
	s_barrier
	s_add_i32 s24, s25, 0x2000
	s_cmpk_lg_i32 s25, 0x4000
	s_cselect_b32 s24, s24, 0
	v_add_u32_e32 v192, s44, v190
	ds_read_b64_tr_b16 v[182:183], v192 offset:24576
	ds_read_b64_tr_b16 v[184:185], v192 offset:25088
	v_add_f32_e32 v52, v100, v101
	v_add_f32_e32 v52, v102, v52
	v_add_f32_e32 v52, v103, v52
	v_add_f32_e32 v52, v104, v52
	v_add_f32_e32 v52, v105, v52
	v_cvt_pk_bf16_f32 v152, v100, v101
	v_cvt_pk_bf16_f32 v153, v102, v103
	s_waitcnt lgkmcnt(9)
	v_mfma_f32_32x32x16_bf16 v[84:99], v[64:67], v[160:163], v[36:51]
	ds_read_b64_tr_b16 v[100:101], v192 offset:28672
	ds_read_b64_tr_b16 v[102:103], v192 offset:29184
	v_add_f32_e32 v52, v106, v52
	v_add_f32_e32 v52, v107, v52
	v_add_f32_e32 v52, v108, v52
	v_add_f32_e32 v132, v109, v52
	v_cvt_pk_bf16_f32 v154, v104, v105
	v_cvt_pk_bf16_f32 v155, v106, v107
	s_waitcnt lgkmcnt(10)
	v_mfma_f32_32x32x16_bf16 v[52:67], v[124:127], v[160:163], v[36:51]
	ds_read_b64_tr_b16 v[104:105], v192 offset:25600
	ds_read_b64_tr_b16 v[106:107], v192 offset:26112
	v_add_f32_e32 v124, v110, v132
	v_add_f32_e32 v124, v111, v124
	v_add_f32_e32 v124, v112, v124
	v_add_f32_e32 v124, v113, v124
	v_cvt_pk_bf16_f32 v148, v108, v109
	v_cvt_pk_bf16_f32 v149, v110, v111
	s_waitcnt lgkmcnt(11)
	v_mfma_f32_32x32x16_bf16 v[84:99], v[128:131], v[156:159], v[84:99]
	ds_read_b64_tr_b16 v[108:109], v192 offset:29696
	ds_read_b64_tr_b16 v[110:111], v192 offset:30208
	v_add_f32_e32 v124, v114, v124
	v_add_f32_e32 v124, v115, v124
	v_add_f32_e32 v124, v68, v124
	v_add_f32_e32 v124, v69, v124
	v_cvt_pk_bf16_f32 v150, v112, v113
	v_cvt_pk_bf16_f32 v151, v114, v115
	s_waitcnt lgkmcnt(12)
	v_mfma_f32_32x32x16_bf16 v[52:67], v[164:167], v[156:159], v[52:67]
	ds_read_b64_tr_b16 v[112:113], v192 offset:26624
	ds_read_b64_tr_b16 v[114:115], v192 offset:27136
	v_add_f32_e32 v124, v70, v124
	v_add_f32_e32 v124, v71, v124
	v_add_f32_e32 v124, v72, v124
	v_add_f32_e32 v124, v73, v124
	v_cvt_pk_bf16_f32 v140, v68, v69
	v_cvt_pk_bf16_f32 v141, v70, v71
	s_waitcnt lgkmcnt(13)
	v_mfma_f32_32x32x16_bf16 v[84:99], v[168:171], v[144:147], v[84:99]
	ds_read_b64_tr_b16 v[68:69], v192 offset:30720
	ds_read_b64_tr_b16 v[70:71], v192 offset:31232
	v_add_f32_e32 v124, v74, v124
	v_add_f32_e32 v124, v75, v124
	v_add_f32_e32 v124, v76, v124
	v_add_f32_e32 v124, v77, v124
	v_cvt_pk_bf16_f32 v142, v72, v73
	v_cvt_pk_bf16_f32 v143, v74, v75
	s_waitcnt lgkmcnt(14)
	v_mfma_f32_32x32x16_bf16 v[52:67], v[172:175], v[144:147], v[52:67]
	ds_read_b64_tr_b16 v[72:73], v192 offset:27648
	ds_read_b64_tr_b16 v[74:75], v192 offset:28160
	s_waitcnt lgkmcnt(14)
	v_mfma_f32_32x32x16_bf16 v[84:99], v[120:123], v[136:139], v[84:99]
	v_add_f32_e32 v120, v78, v124
	v_add_f32_e32 v120, v79, v120
	v_add_f32_e32 v120, v80, v120
	v_add_f32_e32 v120, v81, v120
	v_cvt_pk_bf16_f32 v132, v76, v77
	v_cvt_pk_bf16_f32 v133, v78, v79
	ds_read_b64_tr_b16 v[76:77], v192 offset:31744
	ds_read_b64_tr_b16 v[78:79], v192 offset:32256
	v_mfma_f32_32x32x16_bf16 v[52:67], v[116:119], v[136:139], v[52:67]
	v_add_f32_e32 v116, v82, v120
	v_add_f32_e32 v116, v83, v116
	v_add_f32_e32 v116, 0, v116
	v_cvt_pk_bf16_f32 v134, v80, v81
	v_cvt_pk_bf16_f32 v135, v82, v83
	s_add_i32 s29, s24, s58
	v_lshl_add_u64 v[80:81], v[180:181], 0, s[60:61]
	s_mov_b32 s44, m0
	s_mov_b32 m0, s29
	s_nop 0
	global_load_lds_dwordx4 v[80:81], off
	s_mov_b32 m0, s44
	v_add_f32_e32 v1, v1, v116
	s_waitcnt lgkmcnt(14)
	v_mfma_f32_32x32x16_bf16 v[4:19], v[152:155], v[182:185], v[4:19]
	v_exp_f32_e32 v84, v84
	v_exp_f32_e32 v85, v85
	v_exp_f32_e32 v86, v86
	v_exp_f32_e32 v87, v87
	s_waitcnt lgkmcnt(12)
	v_mfma_f32_32x32x16_bf16 v[20:35], v[152:155], v[100:103], v[20:35]
	v_exp_f32_e32 v88, v88
	v_exp_f32_e32 v89, v89
	v_exp_f32_e32 v90, v90
	v_exp_f32_e32 v91, v91
	v_add_u32_e32 v80, s24, v191
	ds_read_b128 v[116:119], v80
	ds_read_b128 v[120:123], v80 offset:512
	s_waitcnt lgkmcnt(12)
	v_mfma_f32_32x32x16_bf16 v[4:19], v[148:151], v[104:107], v[4:19]
	v_exp_f32_e32 v92, v92
	v_exp_f32_e32 v93, v93
	v_exp_f32_e32 v94, v94
	v_exp_f32_e32 v95, v95
	ds_read_b128 v[104:107], v80 offset:2048
	ds_read_b128 v[124:127], v80 offset:2560
	s_waitcnt lgkmcnt(12)
	v_mfma_f32_32x32x16_bf16 v[20:35], v[148:151], v[108:111], v[20:35]
	v_exp_f32_e32 v96, v96
	v_exp_f32_e32 v97, v97
	v_exp_f32_e32 v98, v98
	v_exp_f32_e32 v99, v99
	ds_read_b128 v[108:111], v80 offset:4096
	ds_read_b128 v[128:131], v80 offset:4608
	s_waitcnt lgkmcnt(12)
	v_mfma_f32_32x32x16_bf16 v[4:19], v[140:143], v[112:115], v[4:19]
	v_exp_f32_e32 v52, v52
	v_exp_f32_e32 v53, v53
	v_exp_f32_e32 v54, v54
	v_exp_f32_e32 v55, v55
	ds_read_b128 v[112:115], v80 offset:6144
	ds_read_b128 v[100:103], v80 offset:6656
	s_waitcnt lgkmcnt(12)
	v_mfma_f32_32x32x16_bf16 v[20:35], v[140:143], v[68:71], v[20:35]
	v_exp_f32_e32 v56, v56
	v_exp_f32_e32 v57, v57
	v_exp_f32_e32 v58, v58
	v_exp_f32_e32 v59, v59
	s_waitcnt lgkmcnt(10)
	v_mfma_f32_32x32x16_bf16 v[4:19], v[132:135], v[72:75], v[4:19]
	v_exp_f32_e32 v60, v60
	v_exp_f32_e32 v61, v61
	v_exp_f32_e32 v62, v62
	v_exp_f32_e32 v63, v63
	s_waitcnt lgkmcnt(8)
	v_mfma_f32_32x32x16_bf16 v[20:35], v[132:135], v[76:79], v[20:35]
	v_exp_f32_e32 v64, v64
	v_exp_f32_e32 v65, v65
	v_exp_f32_e32 v66, v66
	v_exp_f32_e32 v67, v67
	s_waitcnt vmcnt(0) lgkmcnt(0)
	s_barrier
	v_add_u32_e32 v168, s25, v190
	ds_read_b64_tr_b16 v[164:165], v168 offset:24576
	ds_read_b64_tr_b16 v[166:167], v168 offset:25088
	v_add_f32_e32 v68, v84, v85
	v_add_f32_e32 v68, v86, v68
	v_add_f32_e32 v68, v87, v68
	v_add_f32_e32 v68, v88, v68
	v_add_f32_e32 v132, v89, v68
	v_cvt_pk_bf16_f32 v152, v84, v85
	v_cvt_pk_bf16_f32 v153, v86, v87
	s_waitcnt lgkmcnt(9)
	v_mfma_f32_32x32x16_bf16 v[68:83], v[116:119], v[160:163], v[36:51]
	ds_read_b64_tr_b16 v[84:85], v168 offset:28672
	ds_read_b64_tr_b16 v[86:87], v168 offset:29184
	v_add_f32_e32 v116, v90, v132
	v_add_f32_e32 v116, v91, v116
	v_add_f32_e32 v116, v92, v116
	v_add_f32_e32 v116, v93, v116
	v_cvt_pk_bf16_f32 v154, v88, v89
	v_cvt_pk_bf16_f32 v155, v90, v91
	s_waitcnt lgkmcnt(10)
	v_mfma_f32_32x32x16_bf16 v[36:51], v[120:123], v[160:163], v[36:51]
	ds_read_b64_tr_b16 v[88:89], v168 offset:25600
	ds_read_b64_tr_b16 v[90:91], v168 offset:26112
	s_waitcnt lgkmcnt(11)
	v_mfma_f32_32x32x16_bf16 v[68:83], v[104:107], v[156:159], v[68:83]
	v_add_f32_e32 v104, v94, v116
	v_add_f32_e32 v104, v95, v104
	v_add_f32_e32 v104, v96, v104
	v_add_f32_e32 v104, v97, v104
	v_cvt_pk_bf16_f32 v148, v92, v93
	v_cvt_pk_bf16_f32 v149, v94, v95
	ds_read_b64_tr_b16 v[92:93], v168 offset:29696
	ds_read_b64_tr_b16 v[94:95], v168 offset:30208
	v_add_f32_e32 v104, v98, v104
	v_add_f32_e32 v104, v99, v104
	v_add_f32_e32 v104, v52, v104
	v_add_f32_e32 v104, v53, v104
	v_cvt_pk_bf16_f32 v150, v96, v97
	v_cvt_pk_bf16_f32 v151, v98, v99
	s_waitcnt lgkmcnt(12)
	v_mfma_f32_32x32x16_bf16 v[36:51], v[124:127], v[156:159], v[36:51]
	ds_read_b64_tr_b16 v[96:97], v168 offset:26624
	ds_read_b64_tr_b16 v[98:99], v168 offset:27136
	v_add_f32_e32 v104, v54, v104
	v_add_f32_e32 v104, v55, v104
	v_add_f32_e32 v104, v56, v104
	v_add_f32_e32 v104, v57, v104
	v_cvt_pk_bf16_f32 v140, v52, v53
	v_cvt_pk_bf16_f32 v141, v54, v55
	s_waitcnt lgkmcnt(13)
	v_mfma_f32_32x32x16_bf16 v[68:83], v[108:111], v[144:147], v[68:83]
	ds_read_b64_tr_b16 v[52:53], v168 offset:30720
	ds_read_b64_tr_b16 v[54:55], v168 offset:31232
	v_add_f32_e32 v104, v58, v104
	v_add_f32_e32 v104, v59, v104
	v_add_f32_e32 v104, v60, v104
	v_add_f32_e32 v104, v61, v104
	v_cvt_pk_bf16_f32 v142, v56, v57
	v_cvt_pk_bf16_f32 v143, v58, v59
	s_waitcnt lgkmcnt(14)
	v_mfma_f32_32x32x16_bf16 v[36:51], v[128:131], v[144:147], v[36:51]
	ds_read_b64_tr_b16 v[56:57], v168 offset:27648
	ds_read_b64_tr_b16 v[58:59], v168 offset:28160
	v_add_f32_e32 v104, v62, v104
	v_add_f32_e32 v104, v63, v104
	v_add_f32_e32 v104, v64, v104
	v_add_f32_e32 v104, v65, v104
	v_cvt_pk_bf16_f32 v132, v60, v61
	v_cvt_pk_bf16_f32 v133, v62, v63
	s_waitcnt lgkmcnt(14)
	v_mfma_f32_32x32x16_bf16 v[68:83], v[112:115], v[136:139], v[68:83]
	ds_read_b64_tr_b16 v[60:61], v168 offset:31744
	ds_read_b64_tr_b16 v[62:63], v168 offset:32256
	v_mfma_f32_32x32x16_bf16 v[36:51], v[100:103], v[136:139], v[36:51]
	v_add_f32_e32 v100, v66, v104
	v_add_f32_e32 v100, v67, v100
	v_add_f32_e32 v100, 0, v100
	v_cvt_pk_bf16_f32 v134, v64, v65
	v_cvt_pk_bf16_f32 v135, v66, v67
	s_waitcnt lgkmcnt(14)
	v_mfma_f32_32x32x16_bf16 v[4:19], v[152:155], v[164:167], v[4:19]
	s_nop 1
	v_exp_f32_e32 v68, v68
	v_exp_f32_e32 v69, v69
	v_exp_f32_e32 v70, v70
	v_exp_f32_e32 v71, v71
	s_waitcnt lgkmcnt(12)
	v_mfma_f32_32x32x16_bf16 v[20:35], v[152:155], v[84:87], v[20:35]
	v_exp_f32_e32 v72, v72
	v_exp_f32_e32 v73, v73
	v_exp_f32_e32 v74, v74
	v_exp_f32_e32 v75, v75
	s_waitcnt lgkmcnt(10)
	v_mfma_f32_32x32x16_bf16 v[4:19], v[148:151], v[88:91], v[4:19]
	v_exp_f32_e32 v76, v76
	v_exp_f32_e32 v77, v77
	v_exp_f32_e32 v78, v78
	v_exp_f32_e32 v79, v79
	s_waitcnt lgkmcnt(8)
	v_mfma_f32_32x32x16_bf16 v[20:35], v[148:151], v[92:95], v[20:35]
	v_exp_f32_e32 v80, v80
	v_exp_f32_e32 v81, v81
	v_exp_f32_e32 v82, v82
	v_exp_f32_e32 v83, v83
	s_waitcnt lgkmcnt(6)
	v_mfma_f32_32x32x16_bf16 v[4:19], v[140:143], v[96:99], v[4:19]
	v_exp_f32_e32 v36, v36
	v_exp_f32_e32 v37, v37
	v_exp_f32_e32 v38, v38
	v_exp_f32_e32 v39, v39
	s_waitcnt lgkmcnt(4)
	v_mfma_f32_32x32x16_bf16 v[20:35], v[140:143], v[52:55], v[20:35]
	v_exp_f32_e32 v40, v40
	v_exp_f32_e32 v41, v41
	v_exp_f32_e32 v42, v42
	v_exp_f32_e32 v43, v43
	s_waitcnt lgkmcnt(2)
	v_mfma_f32_32x32x16_bf16 v[4:19], v[132:135], v[56:59], v[4:19]
	v_exp_f32_e32 v44, v44
	v_exp_f32_e32 v45, v45
	v_exp_f32_e32 v46, v46
	v_exp_f32_e32 v47, v47
	s_waitcnt lgkmcnt(0)
	v_mfma_f32_32x32x16_bf16 v[20:35], v[132:135], v[60:63], v[20:35]
	v_exp_f32_e32 v48, v48
	v_exp_f32_e32 v49, v49
	v_exp_f32_e32 v50, v50
	v_exp_f32_e32 v51, v51
	v_add_f32_e32 v52, v68, v69
	v_add_f32_e32 v52, v70, v52
	v_add_f32_e32 v52, v71, v52
	v_add_f32_e32 v52, v72, v52
	v_add_f32_e32 v52, v73, v52
	v_add_f32_e32 v52, v74, v52
	v_add_f32_e32 v52, v75, v52
	v_add_f32_e32 v52, v76, v52
	v_add_f32_e32 v52, v77, v52
	v_add_f32_e32 v52, v78, v52
	v_add_f32_e32 v52, v79, v52
	v_add_f32_e32 v52, v80, v52
	v_add_f32_e32 v52, v81, v52
	v_add_f32_e32 v52, v82, v52
	v_add_f32_e32 v52, v83, v52
	v_add_f32_e32 v52, v36, v52
	v_add_f32_e32 v52, v37, v52
	v_add_f32_e32 v52, v38, v52
	v_add_f32_e32 v52, v39, v52
	v_add_f32_e32 v52, v40, v52
	v_add_f32_e32 v52, v41, v52
	v_add_f32_e32 v52, v42, v52
	v_add_f32_e32 v52, v43, v52
	v_add_f32_e32 v52, v44, v52
	v_add_f32_e32 v52, v45, v52
	v_add_f32_e32 v52, v46, v52
	v_add_f32_e32 v52, v47, v52
	v_add_f32_e32 v52, v48, v52
	v_add_f32_e32 v52, v49, v52
	v_add_f32_e32 v52, v50, v52
	v_add_f32_e32 v52, v51, v52
	v_add_f32_e32 v1, v1, v100
	v_add_f32_e32 v1, v1, v52
	v_cvt_pk_bf16_f32 v52, v68, v69
	v_cvt_pk_bf16_f32 v53, v70, v71
	v_cvt_pk_bf16_f32 v54, v72, v73
	v_cvt_pk_bf16_f32 v55, v74, v75
	v_cvt_pk_bf16_f32 v56, v76, v77
	v_cvt_pk_bf16_f32 v57, v78, v79
	v_cvt_pk_bf16_f32 v58, v80, v81
	v_cvt_pk_bf16_f32 v59, v82, v83
	v_cvt_pk_bf16_f32 v36, v36, v37
	v_cvt_pk_bf16_f32 v37, v38, v39
	v_cvt_pk_bf16_f32 v38, v40, v41
	v_cvt_pk_bf16_f32 v39, v42, v43
	v_cvt_pk_bf16_f32 v40, v44, v45
	v_cvt_pk_bf16_f32 v41, v46, v47
	v_cvt_pk_bf16_f32 v42, v48, v49
	v_cvt_pk_bf16_f32 v43, v50, v51
	v_add3_u32 v0, v0, v3, s24
	ds_read_b64_tr_b16 v[44:45],v0 offset:0
	ds_read_b64_tr_b16 v[46:47],v0 offset:512
	ds_read_b64_tr_b16 v[48:49],v0 offset:1024
	ds_read_b64_tr_b16 v[50:51],v0 offset:1536
	ds_read_b64_tr_b16 v[60:61],v0 offset:2048
	ds_read_b64_tr_b16 v[62:63],v0 offset:2560
	ds_read_b64_tr_b16 v[64:65],v0 offset:3072
	ds_read_b64_tr_b16 v[66:67],v0 offset:3584
	s_waitcnt lgkmcnt(0)
	s_nop 0
	v_mfma_f32_32x32x16_bf16 v[4:19], v[52:55], v[44:47], v[4:19]
	ds_read_b64_tr_b16 v[44:45],v0 offset:4096
	ds_read_b64_tr_b16 v[46:47],v0 offset:4608
	v_mfma_f32_32x32x16_bf16 v[4:19], v[56:59], v[48:51], v[4:19]
	ds_read_b64_tr_b16 v[48:49],v0 offset:5120
	ds_read_b64_tr_b16 v[50:51],v0 offset:5632
	v_mfma_f32_32x32x16_bf16 v[4:19], v[36:39], v[60:63], v[4:19]
	ds_read_b64_tr_b16 v[60:61],v0 offset:6144
	ds_read_b64_tr_b16 v[62:63],v0 offset:6656
	v_mfma_f32_32x32x16_bf16 v[4:19], v[40:43], v[64:67], v[4:19]
	ds_read_b64_tr_b16 v[64:65],v0 offset:7168
	ds_read_b64_tr_b16 v[66:67],v0 offset:7680
	s_waitcnt lgkmcnt(0)
	v_mfma_f32_32x32x16_bf16 v[20:35], v[52:55], v[44:47], v[20:35]
	v_mfma_f32_32x32x16_bf16 v[20:35], v[56:59], v[48:51], v[20:35]
	v_mfma_f32_32x32x16_bf16 v[20:35], v[36:39], v[60:63], v[20:35]
	v_mfma_f32_32x32x16_bf16 v[20:35], v[40:43], v[64:67], v[20:35]
	s_setprio 0
	v_mov_b32_e32 v0, v1
	s_nop 1
	v_permlane32_swap_b32_e32 v1, v0
	v_cmp_gt_u32_e32 vcc, 32, v186
	s_and_saveexec_b64 s[24:25], vcc
	s_cbranch_execz .LBB0_727
	v_lshl_add_u32 v3, v188, 2, s28
	v_add_f32_e32 v0, v1, v0
	ds_write_b32 v3, v0 offset:49280
	s_branch .LBB0_727

	.amdhsa_kernel _Z10fwd_kernel6Params
		.amdhsa_group_segment_fixed_size 0
		.amdhsa_private_segment_fixed_size 0
		.amdhsa_kernarg_size 408
		.amdhsa_user_sgpr_count 2
		.amdhsa_user_sgpr_dispatch_ptr 0
		.amdhsa_user_sgpr_queue_ptr 0
		.amdhsa_user_sgpr_kernarg_segment_ptr 1
		.amdhsa_user_sgpr_dispatch_id 0
		.amdhsa_user_sgpr_kernarg_preload_length 0
		.amdhsa_user_sgpr_kernarg_preload_offset 0
		.amdhsa_user_sgpr_private_segment_size 0
		.amdhsa_uses_dynamic_stack 0
		.amdhsa_enable_private_segment 0
		.amdhsa_system_sgpr_workgroup_id_x 1
		.amdhsa_system_sgpr_workgroup_id_y 0
		.amdhsa_system_sgpr_workgroup_id_z 0
		.amdhsa_system_sgpr_workgroup_info 0
		.amdhsa_system_vgpr_workitem_id 2
		.amdhsa_next_free_vgpr 256
		.amdhsa_next_free_sgpr 102
		.amdhsa_accum_offset 256
		.amdhsa_reserve_vcc 1
		.amdhsa_float_round_mode_32 0
		.amdhsa_float_round_mode_16_64 0
		.amdhsa_float_denorm_mode_32 3
		.amdhsa_float_denorm_mode_16_64 3
		.amdhsa_dx10_clamp 1
		.amdhsa_ieee_mode 1
		.amdhsa_fp16_overflow 0
		.amdhsa_tg_split 0
		.amdhsa_exception_fp_ieee_invalid_op 0
		.amdhsa_exception_fp_denorm_src 0
		.amdhsa_exception_fp_ieee_div_zero 0
		.amdhsa_exception_fp_ieee_overflow 0
		.amdhsa_exception_fp_ieee_underflow 0
		.amdhsa_exception_fp_ieee_inexact 0
		.amdhsa_exception_int_div_zero 0
	.end_amdhsa_kernel

amdhsa.kernels:
  - .agpr_count:     0
    .args:
      - .offset:         0
        .size:           152
        .value_kind:     by_value
      - .offset:         152
        .size:           4
        .value_kind:     hidden_block_count_x
      - .offset:         156
        .size:           4
        .value_kind:     hidden_block_count_y
      - .offset:         160
        .size:           4
        .value_kind:     hidden_block_count_z
      - .offset:         164
        .size:           2
        .value_kind:     hidden_group_size_x
      - .offset:         166
        .size:           2
        .value_kind:     hidden_group_size_y
      - .offset:         168
        .size:           2
        .value_kind:     hidden_group_size_z
      - .offset:         170
        .size:           2
        .value_kind:     hidden_remainder_x
      - .offset:         172
        .size:           2
        .value_kind:     hidden_remainder_y
      - .offset:         174
        .size:           2
        .value_kind:     hidden_remainder_z
      - .offset:         192
        .size:           8
        .value_kind:     hidden_global_offset_x
      - .offset:         200
        .size:           8
        .value_kind:     hidden_global_offset_y
      - .offset:         208
        .size:           8
        .value_kind:     hidden_global_offset_z
      - .offset:         216
        .size:           2
        .value_kind:     hidden_grid_dims
      - .offset:         240
        .size:           8
        .value_kind:     hidden_multigrid_sync_arg
      - .offset:         272
        .size:           4
        .value_kind:     hidden_dynamic_lds_size
    .group_segment_fixed_size: 0
    .kernarg_segment_align: 8
    .kernarg_segment_size: 408
    .language:       OpenCL C
    .language_version:
      - 2
      - 0
    .max_flat_workgroup_size: 512
    .name:           _Z10fwd_kernel6Params
    .private_segment_fixed_size: 0
    .sgpr_count:     108
    .sgpr_spill_count: 125
    .symbol:         _Z10fwd_kernel6Params.kd
    .uniform_work_group_size: 1
    .uses_dynamic_stack: false
    .vgpr_count:     256
    .vgpr_spill_count: 0
    .wavefront_size: 64
